# byte-placement trial: selective-nt version shifted by 16 bytes (4 nops at entry)
# baseline (speedup 1.0000x reference)
; DI unsigned xb_add(unsigned* p, unsigned v) { return __hip_atomic_fetch_add(p, v, __ATOMIC_RELAXED, __HIP_MEMORY_SCOPE_AGENT); }
; DI unsigned xb_xcc_id() { return (unsigned)__builtin_amdgcn_s_getreg((3 << 11) | 20) & 0xFu; }
; __global__ void __launch_bounds__(256, 2) mega_kernel(KArgs ka) {
;   __shared__ __attribute__((aligned(16))) char smem[SMEM_BYTES];
;   __shared__ uint4 xb_words;
;   cg::grid_group grid = cg::this_grid();
;   const int tid = threadIdx.x;
;   unsigned* const bar = (unsigned*)(ka.ws + OFF_BAR);
;   if (tid == 0) xb_words = make_uint4(0u, 0u, 0u, 0u);
;   if (ka.ws == nullptr) grid.sync();
;   if (tid == 0) (void)xb_add(&((unsigned*)(ka.ws + OFF_BAR))[XB_XCNT(xb_xcc_id())], 1u);
_Z11mega_kernel5KArgs:
	s_nop 0
	s_nop 0
	s_nop 0
	s_nop 0
	s_load_dwordx2 s[96:97], s[0:1], 0xd0
	s_load_dwordx4 s[16:19], s[0:1], 0xc0
	s_add_u32 s4, s0, 0xd8
	v_and_b32_e32 v206, 0x3ff, v0
	s_mov_b32 s48, s2
	s_addc_u32 s5, s1, 0
	v_cmp_eq_u32_e64 s[92:93], 0, v206
	s_and_saveexec_b64 s[2:3], s[92:93]
	s_cbranch_execnz .LBB0_3
	s_or_b64 exec, exec, s[2:3]
	s_load_dword s49, s[0:1], 0xd8
	s_waitcnt lgkmcnt(0)
	s_cmp_lg_u64 s[96:97], 0
	s_cbranch_scc0 .LBB0_4
